# ffn-up tile scheduler also resumes its patch scan after the current unit (in-proj already does): no O(unit index) SALU rescan before each K-loop
# speedup vs baseline: 1.0264x; 1.0112x over previous
.LBB0_41:
	s_mov_b64 s[56:57], s[44:45]
	s_mov_b64 s[58:59], s[46:47]
	s_mov_b32 s30, s34
	s_mov_b32 s54, s95
	s_mov_b32 s51, s50
	s_add_i32 s50, s50, 1
	s_mov_b32 s61, -1
	s_mov_b32 s55, 0
	s_mov_b32 s0, 0
	s_mov_b32 s1, 0
	s_cmp_eq_u32 s51, 0
	s_cbranch_scc1 .Lsr_fu
	s_mov_b32 s61, s51
	s_mov_b32 s1, s100
	s_mov_b32 s0, s100
	s_lshr_b32 s55, s100, 3
	s_mul_i32 s55, s55, s94
.Lsr_fu:
.LBB0_42:
	s_mov_b32 s22, s90
	s_and_b64 vcc, exec, s[40:41]
	s_mov_b64 s[64:65], -1
	s_cbranch_vccnz .LBB0_45
	s_add_i32 s39, s22, s55
	s_mov_b64 s[64:65], 0
	s_cmpk_gt_i32 s39, 0x18bf
	s_mov_b64 s[20:21], 0
	s_mov_b32 s62, s63
	s_mov_b32 s60, s37
	s_cbranch_scc1 .LBB0_45
	s_mul_hi_i32 s20, s39, 0x2e8ba2e9
	s_lshr_b32 s21, s20, 31
	s_ashr_i32 s20, s20, 2
	s_add_i32 s60, s20, s21
	s_mul_i32 s20, s60, 0xffffffea
	s_add_i32 s62, s39, s20
	s_mov_b64 s[20:21], -1

.LBB0_57:
	s_mov_b32 s100, s1
	s_and_b64 s[0:1], s[52:53], exec
	s_cselect_b32 s20, s45, s57
	s_cselect_b32 s21, s44, s56
	s_cselect_b32 s51, s47, s59
	s_cselect_b32 s55, s46, s58
	s_add_u32 s56, s56, 0x40080
	s_addc_u32 s57, s57, 0
	s_add_u32 s62, s58, 0x100
	v_mov_b32_e32 v0, 0
	s_addc_u32 s63, s59, 0
	s_mov_b32 s64, -2
	v_mov_b32_e32 v1, v0
	v_mov_b32_e32 v2, v0
	v_mov_b32_e32 v3, v0
	v_mov_b32_e32 v8, v0
	v_mov_b32_e32 v9, v0
	v_mov_b32_e32 v10, v0
	v_mov_b32_e32 v11, v0
	v_mov_b32_e32 v16, v0
	v_mov_b32_e32 v17, v0
	v_mov_b32_e32 v18, v0
	v_mov_b32_e32 v19, v0
	v_mov_b32_e32 v24, v0
	v_mov_b32_e32 v25, v0
	v_mov_b32_e32 v26, v0
	v_mov_b32_e32 v27, v0
	v_mov_b32_e32 v32, v0
	v_mov_b32_e32 v33, v0
	v_mov_b32_e32 v34, v0
	v_mov_b32_e32 v35, v0
	v_mov_b32_e32 v40, v0
	v_mov_b32_e32 v41, v0
	v_mov_b32_e32 v42, v0
	v_mov_b32_e32 v43, v0
	v_mov_b32_e32 v48, v0
	v_mov_b32_e32 v49, v0
	v_mov_b32_e32 v50, v0
	v_mov_b32_e32 v51, v0
	v_mov_b32_e32 v56, v0
	v_mov_b32_e32 v57, v0
	v_mov_b32_e32 v58, v0
	v_mov_b32_e32 v59, v0
	v_mov_b32_e32 v4, v0
	v_mov_b32_e32 v5, v0
	v_mov_b32_e32 v6, v0
	v_mov_b32_e32 v7, v0
	v_mov_b32_e32 v12, v0
	v_mov_b32_e32 v13, v0
	v_mov_b32_e32 v14, v0
	v_mov_b32_e32 v15, v0
	v_mov_b32_e32 v20, v0
	v_mov_b32_e32 v21, v0
	v_mov_b32_e32 v22, v0
	v_mov_b32_e32 v23, v0
	v_mov_b32_e32 v28, v0
	v_mov_b32_e32 v29, v0
	v_mov_b32_e32 v30, v0
	v_mov_b32_e32 v31, v0
	v_mov_b32_e32 v36, v0
	v_mov_b32_e32 v37, v0
	v_mov_b32_e32 v38, v0
	v_mov_b32_e32 v39, v0
	v_mov_b32_e32 v44, v0
	v_mov_b32_e32 v45, v0
	v_mov_b32_e32 v46, v0
	v_mov_b32_e32 v47, v0
	v_mov_b32_e32 v52, v0
	v_mov_b32_e32 v53, v0
	v_mov_b32_e32 v54, v0
	v_mov_b32_e32 v55, v0
	v_mov_b32_e32 v60, v0
	v_mov_b32_e32 v61, v0
	v_mov_b32_e32 v62, v0
	v_mov_b32_e32 v63, v0
	v_mov_b32_e32 v64, v0
	v_mov_b32_e32 v65, v0
	v_mov_b32_e32 v66, v0
	v_mov_b32_e32 v67, v0
	v_mov_b32_e32 v72, v0
	v_mov_b32_e32 v73, v0
	v_mov_b32_e32 v74, v0
	v_mov_b32_e32 v75, v0
	v_mov_b32_e32 v80, v0
	v_mov_b32_e32 v81, v0
	v_mov_b32_e32 v82, v0
	v_mov_b32_e32 v83, v0
	v_mov_b32_e32 v88, v0
	v_mov_b32_e32 v89, v0
	v_mov_b32_e32 v90, v0
	v_mov_b32_e32 v91, v0
	v_mov_b32_e32 v96, v0
	v_mov_b32_e32 v97, v0
	v_mov_b32_e32 v98, v0
	v_mov_b32_e32 v99, v0
	v_mov_b32_e32 v104, v0
	v_mov_b32_e32 v105, v0
	v_mov_b32_e32 v106, v0
	v_mov_b32_e32 v107, v0
	v_mov_b32_e32 v112, v0
	v_mov_b32_e32 v113, v0
	v_mov_b32_e32 v114, v0
	v_mov_b32_e32 v115, v0
	v_mov_b32_e32 v120, v0
	v_mov_b32_e32 v121, v0
	v_mov_b32_e32 v122, v0
	v_mov_b32_e32 v123, v0
	v_mov_b32_e32 v68, v0
	v_mov_b32_e32 v69, v0
	v_mov_b32_e32 v70, v0
	v_mov_b32_e32 v71, v0
	v_mov_b32_e32 v76, v0
	v_mov_b32_e32 v77, v0
	v_mov_b32_e32 v78, v0
	v_mov_b32_e32 v79, v0
	v_mov_b32_e32 v84, v0
	v_mov_b32_e32 v85, v0
	v_mov_b32_e32 v86, v0
	v_mov_b32_e32 v87, v0
	v_mov_b32_e32 v92, v0
	v_mov_b32_e32 v93, v0
	v_mov_b32_e32 v94, v0
	v_mov_b32_e32 v95, v0
	v_mov_b32_e32 v100, v0
	v_mov_b32_e32 v101, v0
	v_mov_b32_e32 v102, v0
	v_mov_b32_e32 v103, v0
	v_mov_b32_e32 v108, v0
	v_mov_b32_e32 v109, v0
	v_mov_b32_e32 v110, v0
	v_mov_b32_e32 v111, v0
	v_mov_b32_e32 v116, v0
	v_mov_b32_e32 v117, v0
	v_mov_b32_e32 v118, v0
	v_mov_b32_e32 v119, v0
	v_mov_b32_e32 v124, v0
	v_mov_b32_e32 v125, v0
	v_mov_b32_e32 v126, v0
	v_mov_b32_e32 v127, v0
